# layer-0 p->bf16 conversion moved from the attention phase's tail (all CUs, exposed) into the out-proj third-round slot of CUs bid>=16, all loads in flight before the first store
# speedup vs baseline: 1.0140x; 1.0140x over previous
; __device__ __forceinline__ void convert_flat(const float* src, bf16* dst, size_t n, size_t gtid, size_t gthreads) {
;     for (size_t i = gtid * 8; i < n; i += gthreads * 8) {
;         const f32x4 a = *(const f32x4*)(src + i), b = *(const f32x4*)(src + i + 4);
;     bf16* PB = (bf16*)(ws + WS_PB);
;     if (part & 1) {
;     convert_flat(I.p_p + (size_t)l * MP * DPLE, PB + (size_t)l * MT * DPLE, (size_t)MP * DPLE, gtid, gth);
;     convert_flat(I.p_s + (size_t)l * MS * DPLE, PB + (size_t)l * MT * DPLE + (size_t)MP * DPLE, (size_t)MS * DPLE, gtid, gth);
.LBB0_412:
	v_readlane_b32 s0, v249, 59
	v_readlane_b32 s2, v249, 17
	v_mov_b32_e32 v0, v196
	v_readlane_b32 s1, v249, 60
	v_readlane_b32 s3, v249, 18
	s_add_u32 s0, s2, s0
	s_waitcnt vmcnt(63) expcnt(7) lgkmcnt(15)
	s_barrier
	s_addc_u32 s1, s3, s1
	v_ashrrev_i32_e32 v1, 31, v0
	v_lshl_add_u64 v[2:3], s[0:1], 0, v[0:1]
	v_lshlrev_b64 v[0:1], 3, v[2:3]
	s_mov_b64 s[0:1], 0x800000
	s_lshl_b64 s[6:7], s[64:65], 12
	v_cmp_gt_u64_e32 vcc, s[0:1], v[0:1]
	v_lshlrev_b64 v[4:5], 5, v[2:3]
	v_lshl_add_u64 v[2:3], v[2:3], 4, s[44:45]
	s_cmp_lg_u32 s64, 0x100
	s_cbranch_scc1 .Lcvp_orig1
	v_writelane_b32 v250, s16, 0
	v_writelane_b32 v250, s17, 1
	v_writelane_b32 v250, s18, 2
	v_writelane_b32 v250, s19, 3
	s_mov_b64 vcc, 0
.Lcvp_orig1:
	s_and_saveexec_b64 s[8:9], vcc
	s_cbranch_execz .LBB0_415
	v_lshl_add_u64 v[6:7], s[16:17], 0, v[4:5]
	s_mov_b64 s[0:1], 0x19080000
	v_lshl_add_u64 v[6:7], v[6:7], 0, 16
	s_lshl_b64 s[10:11], s[64:65], 14
	v_lshl_add_u64 v[8:9], v[2:3], 0, s[0:1]
	s_lshl_b64 s[12:13], s[64:65], 13
	s_mov_b64 s[14:15], 0
	s_mov_b64 s[28:29], 0x7fffff
	v_mov_b64_e32 v[10:11], v[0:1]

; __device__ __forceinline__ void convert_flat(const float* src, bf16* dst, size_t n, size_t gtid, size_t gthreads) {
;     for (size_t i = gtid * 8; i < n; i += gthreads * 8) {
;         const f32x4 a = *(const f32x4*)(src + i), b = *(const f32x4*)(src + i + 4);
;     ...
;     if (part & 1) {
;     convert_flat(I.p_p + (size_t)l * MP * DPLE, PB + (size_t)l * MT * DPLE, (size_t)MP * DPLE, gtid, gth);
;     convert_flat(I.p_s + (size_t)l * MS * DPLE, PB + (size_t)l * MT * DPLE + (size_t)MP * DPLE, (size_t)MS * DPLE, gtid, gth);
.LBB0_415:
	s_or_b64 exec, exec, s[8:9]
	v_readlane_b32 s86, v249, 46
	s_mov_b64 s[0:1], 0x40000
	v_readlane_b32 s87, v249, 47
	v_cmp_gt_u64_e32 vcc, s[0:1], v[0:1]
	s_cmp_lg_u32 s64, 0x100
	s_cbranch_scc1 .Lcvp_orig2
	s_mov_b64 vcc, 0
.Lcvp_orig2:
	s_and_saveexec_b64 s[8:9], vcc
	s_cbranch_execz .LBB0_418
	v_lshl_add_u64 v[4:5], s[18:19], 0, v[4:5]
	s_mov_b64 s[0:1], 0x1a080000
	v_lshl_add_u64 v[4:5], v[4:5], 0, 16
	s_lshl_b64 s[10:11], s[64:65], 14
	v_lshl_add_u64 v[2:3], v[2:3], 0, s[0:1]
	s_lshl_b64 s[12:13], s[64:65], 13
	s_mov_b64 s[14:15], 0
	s_mov_b64 s[28:29], 0x3ffff

; __device__ __forceinline__ unsigned cvt_pk(float lo, float hi) { unsigned r; asm("v_cvt_pk_bf16_f32 %0, %1, %2" : "=v"(r) : "v"(lo), "v"(hi)); return r; }
; __device__ __forceinline__ void convert_flat(const float* src, bf16* dst, size_t n, size_t gtid, size_t gthreads) {
;     for (size_t i = gtid * 8; i < n; i += gthreads * 8) {
;         const f32x4 a = *(const f32x4*)(src + i), b = *(const f32x4*)(src + i + 4);
;         v4u w; w.x = cvt_pk(a[0], a[1]); w.y = cvt_pk(a[2], a[3]); w.z = cvt_pk(b[0], b[1]); w.w = cvt_pk(b[2], b[3]);
;         *(v4u*)(dst + i) = w;
;     }
;     bf16* PB = (bf16*)(ws + WS_PB);
;     if (part & 1) {
;     convert_flat(I.p_p + (size_t)l * MP * DPLE, PB + (size_t)l * MT * DPLE, (size_t)MP * DPLE, gtid, gth);
;     convert_flat(I.p_s + (size_t)l * MS * DPLE, PB + (size_t)l * MT * DPLE + (size_t)MP * DPLE, (size_t)MS * DPLE, gtid, gth);
;     }
.Lcvp_p3:
	s_cmp_lg_u32 s64, 0x100
	s_cbranch_scc1 .LBB0_571
	v_readlane_b32 s9, v249, 46
	v_readlane_b32 s10, v249, 0
	v_readlane_b32 s0, v249, 1
	v_readlane_b32 s1, v249, 2
	v_readlane_b32 s2, v250, 0
	v_readlane_b32 s3, v250, 1
	v_readlane_b32 s12, v250, 2
	v_readlane_b32 s13, v250, 3
	v_mbcnt_lo_u32_b32 v32, -1, 0
	v_mbcnt_hi_u32_b32 v32, -1, v32
	s_nop 3
	s_add_i32 s9, s9, -16
	s_lshl_b32 s9, s9, 3
	s_add_i32 s10, s9, s10
	s_lshl_b32 s9, s10, 6
	v_add_u32_e32 v32, s9, v32
	v_lshlrev_b32_e32 v33, 5, v32
	v_lshlrev_b32_e32 v34, 4, v32
	s_add_u32 s6, s0, 0x19080000
	s_addc_u32 s7, s1, 0
	s_cmp_lt_u32 s10, 0x200
	s_cbranch_scc0 .Lcvp_a
	global_load_dwordx4 v[108:111], v33, s[12:13]
	global_load_dwordx4 v[112:115], v33, s[12:13] offset:16
.Lcvp_a:
	s_cmp_lt_u32 s10, 0x400
	s_cbranch_scc0 .Lcvp_b
	s_add_u32 s54, s2, 0x1e00000
	s_addc_u32 s55, s3, 0
	global_load_dwordx4 v[100:103], v33, s[54:55]
	global_load_dwordx4 v[104:107], v33, s[54:55] offset:16
.Lcvp_b:
	global_load_dwordx4 v[36:39], v33, s[2:3]
	global_load_dwordx4 v[40:43], v33, s[2:3] offset:16
	s_add_u32 s2, s2, 0x3c0000
	s_addc_u32 s3, s3, 0
	global_load_dwordx4 v[44:47], v33, s[2:3]
	global_load_dwordx4 v[48:51], v33, s[2:3] offset:16
	s_add_u32 s2, s2, 0x3c0000
	s_addc_u32 s3, s3, 0
	global_load_dwordx4 v[52:55], v33, s[2:3]
	global_load_dwordx4 v[56:59], v33, s[2:3] offset:16
	s_add_u32 s2, s2, 0x3c0000
	s_addc_u32 s3, s3, 0
	global_load_dwordx4 v[60:63], v33, s[2:3]
	global_load_dwordx4 v[64:67], v33, s[2:3] offset:16
	s_add_u32 s2, s2, 0x3c0000
	s_addc_u32 s3, s3, 0
	global_load_dwordx4 v[68:71], v33, s[2:3]
	global_load_dwordx4 v[72:75], v33, s[2:3] offset:16
	s_add_u32 s2, s2, 0x3c0000
	s_addc_u32 s3, s3, 0
	global_load_dwordx4 v[76:79], v33, s[2:3]
	global_load_dwordx4 v[80:83], v33, s[2:3] offset:16
	s_add_u32 s2, s2, 0x3c0000
	s_addc_u32 s3, s3, 0
	global_load_dwordx4 v[84:87], v33, s[2:3]
	global_load_dwordx4 v[88:91], v33, s[2:3] offset:16
	s_add_u32 s2, s2, 0x3c0000
	s_addc_u32 s3, s3, 0
	global_load_dwordx4 v[92:95], v33, s[2:3]
	global_load_dwordx4 v[96:99], v33, s[2:3] offset:16
	s_add_u32 s2, s2, 0x3c0000
	s_addc_u32 s3, s3, 0
	s_waitcnt vmcnt(14)
	v_cvt_pk_bf16_f32 v36, v36, v37
	v_cvt_pk_bf16_f32 v37, v38, v39
	v_cvt_pk_bf16_f32 v38, v40, v41
	v_cvt_pk_bf16_f32 v39, v42, v43
	global_store_dwordx4 v34, v[36:39], s[6:7]
	s_add_u32 s6, s6, 0x1e0000
	s_addc_u32 s7, s7, 0
	s_waitcnt vmcnt(13)
	v_cvt_pk_bf16_f32 v44, v44, v45
	v_cvt_pk_bf16_f32 v45, v46, v47
	v_cvt_pk_bf16_f32 v46, v48, v49
	v_cvt_pk_bf16_f32 v47, v50, v51
	global_store_dwordx4 v34, v[44:47], s[6:7]
	s_add_u32 s6, s6, 0x1e0000
	s_addc_u32 s7, s7, 0
	s_waitcnt vmcnt(12)
	v_cvt_pk_bf16_f32 v52, v52, v53
	v_cvt_pk_bf16_f32 v53, v54, v55
	v_cvt_pk_bf16_f32 v54, v56, v57
	v_cvt_pk_bf16_f32 v55, v58, v59
	global_store_dwordx4 v34, v[52:55], s[6:7]
	s_add_u32 s6, s6, 0x1e0000
	s_addc_u32 s7, s7, 0
	s_waitcnt vmcnt(11)
	v_cvt_pk_bf16_f32 v60, v60, v61
	v_cvt_pk_bf16_f32 v61, v62, v63
	v_cvt_pk_bf16_f32 v62, v64, v65
	v_cvt_pk_bf16_f32 v63, v66, v67
	global_store_dwordx4 v34, v[60:63], s[6:7]
	s_add_u32 s6, s6, 0x1e0000
	s_addc_u32 s7, s7, 0
	s_waitcnt vmcnt(10)
	v_cvt_pk_bf16_f32 v68, v68, v69
	v_cvt_pk_bf16_f32 v69, v70, v71
	v_cvt_pk_bf16_f32 v70, v72, v73
	v_cvt_pk_bf16_f32 v71, v74, v75
	global_store_dwordx4 v34, v[68:71], s[6:7]
	s_add_u32 s6, s6, 0x1e0000
	s_addc_u32 s7, s7, 0
	s_waitcnt vmcnt(9)
	v_cvt_pk_bf16_f32 v76, v76, v77
	v_cvt_pk_bf16_f32 v77, v78, v79
	v_cvt_pk_bf16_f32 v78, v80, v81
	v_cvt_pk_bf16_f32 v79, v82, v83
	global_store_dwordx4 v34, v[76:79], s[6:7]
	s_add_u32 s6, s6, 0x1e0000
	s_addc_u32 s7, s7, 0
	s_waitcnt vmcnt(8)
	v_cvt_pk_bf16_f32 v84, v84, v85
	v_cvt_pk_bf16_f32 v85, v86, v87
	v_cvt_pk_bf16_f32 v86, v88, v89
	v_cvt_pk_bf16_f32 v87, v90, v91
	global_store_dwordx4 v34, v[84:87], s[6:7]
	s_add_u32 s6, s6, 0x1e0000
	s_addc_u32 s7, s7, 0
	s_waitcnt vmcnt(7)
	v_cvt_pk_bf16_f32 v92, v92, v93
	v_cvt_pk_bf16_f32 v93, v94, v95
	v_cvt_pk_bf16_f32 v94, v96, v97
	v_cvt_pk_bf16_f32 v95, v98, v99
	global_store_dwordx4 v34, v[92:95], s[6:7]
	s_add_u32 s6, s6, 0x1e0000
	s_addc_u32 s7, s7, 0
	s_cmp_lt_u32 s10, 0x400
	s_cbranch_scc0 .Lcvp_c
	v_cvt_pk_bf16_f32 v100, v100, v101
	v_cvt_pk_bf16_f32 v101, v102, v103
	v_cvt_pk_bf16_f32 v102, v104, v105
	v_cvt_pk_bf16_f32 v103, v106, v107
	global_store_dwordx4 v34, v[100:103], s[6:7]
.Lcvp_c:
	s_cmp_lt_u32 s10, 0x200
	s_cbranch_scc0 .LBB0_571
	s_add_u32 s6, s0, 0x1a080000
	s_addc_u32 s7, s1, 0
	v_cvt_pk_bf16_f32 v108, v108, v109
	v_cvt_pk_bf16_f32 v109, v110, v111
	v_cvt_pk_bf16_f32 v110, v112, v113
	v_cvt_pk_bf16_f32 v111, v114, v115
	global_store_dwordx4 v34, v[108:111], s[6:7]

; #define LAS __attribute__((address_space(3)))
; __global__ void __launch_bounds__(NWAVES * 64, 2) mega_fwd(Args args) {
;     extern __shared__ __attribute__((aligned(16))) unsigned char lds_raw[];
;     LAS unsigned char* lds = (LAS unsigned char*)lds_raw;
	.amdhsa_kernel _Z8mega_fwd4Args
		.amdhsa_group_segment_fixed_size 0
		.amdhsa_private_segment_fixed_size 0
		.amdhsa_kernarg_size 440
		.amdhsa_user_sgpr_count 2
		.amdhsa_user_sgpr_dispatch_ptr 0
		.amdhsa_user_sgpr_queue_ptr 0
		.amdhsa_user_sgpr_kernarg_segment_ptr 1
		.amdhsa_user_sgpr_dispatch_id 0
		.amdhsa_user_sgpr_kernarg_preload_length 0
		.amdhsa_user_sgpr_kernarg_preload_offset 0
		.amdhsa_user_sgpr_private_segment_size 0
		.amdhsa_uses_dynamic_stack 0
		.amdhsa_enable_private_segment 0
		.amdhsa_system_sgpr_workgroup_id_x 1
		.amdhsa_system_sgpr_workgroup_id_y 0
		.amdhsa_system_sgpr_workgroup_id_z 0
		.amdhsa_system_sgpr_workgroup_info 0
		.amdhsa_system_vgpr_workitem_id 2
		.amdhsa_next_free_vgpr 252
		.amdhsa_next_free_sgpr 98
		.amdhsa_accum_offset 252
		.amdhsa_reserve_vcc 1
		.amdhsa_float_round_mode_32 0
		.amdhsa_float_round_mode_16_64 0
		.amdhsa_float_denorm_mode_32 3
		.amdhsa_float_denorm_mode_16_64 3
		.amdhsa_dx10_clamp 1
		.amdhsa_ieee_mode 1
		.amdhsa_fp16_overflow 0
		.amdhsa_tg_split 0
		.amdhsa_exception_fp_ieee_invalid_op 0
		.amdhsa_exception_fp_denorm_src 0
		.amdhsa_exception_fp_ieee_div_zero 0
		.amdhsa_exception_fp_ieee_overflow 0
		.amdhsa_exception_fp_ieee_underflow 0
		.amdhsa_exception_fp_ieee_inexact 0
		.amdhsa_exception_int_div_zero 0
	.end_amdhsa_kernel

; #define LAS __attribute__((address_space(3)))
; __global__ void __launch_bounds__(NWAVES * 64, 2) mega_fwd(Args args) {
;     extern __shared__ __attribute__((aligned(16))) unsigned char lds_raw[];
;     LAS unsigned char* lds = (LAS unsigned char*)lds_raw;
amdhsa.kernels:
  - .agpr_count:     0
    .args:
      - .offset:         0
        .size:           184
        .value_kind:     by_value
      - .offset:         184
        .size:           4
        .value_kind:     hidden_block_count_x
      - .offset:         188
        .size:           4
        .value_kind:     hidden_block_count_y
      - .offset:         192
        .size:           4
        .value_kind:     hidden_block_count_z
      - .offset:         196
        .size:           2
        .value_kind:     hidden_group_size_x
      - .offset:         198
        .size:           2
        .value_kind:     hidden_group_size_y
      - .offset:         200
        .size:           2
        .value_kind:     hidden_group_size_z
      - .offset:         202
        .size:           2
        .value_kind:     hidden_remainder_x
      - .offset:         204
        .size:           2
        .value_kind:     hidden_remainder_y
      - .offset:         206
        .size:           2
        .value_kind:     hidden_remainder_z
      - .offset:         224
        .size:           8
        .value_kind:     hidden_global_offset_x
      - .offset:         232
        .size:           8
        .value_kind:     hidden_global_offset_y
      - .offset:         240
        .size:           8
        .value_kind:     hidden_global_offset_z
      - .offset:         248
        .size:           2
        .value_kind:     hidden_grid_dims
      - .offset:         272
        .size:           8
        .value_kind:     hidden_multigrid_sync_arg
      - .offset:         304
        .size:           4
        .value_kind:     hidden_dynamic_lds_size
    .group_segment_fixed_size: 0
    .kernarg_segment_align: 8
    .kernarg_segment_size: 440
    .language:       OpenCL C
    .language_version:
      - 2
      - 0
    .max_flat_workgroup_size: 512
    .name:           _Z8mega_fwd4Args
    .private_segment_fixed_size: 0
    .sgpr_count:     104
    .sgpr_spill_count: 70
    .symbol:         _Z8mega_fwd4Args.kd
    .uniform_work_group_size: 1
    .uses_dynamic_stack: false
    .vgpr_count:     252
    .vgpr_spill_count: 0
    .wavefront_size: 64
